# K/V preparation loop: next item's raw K/V lines touched by dword loads right after the current loads land (L2 warm-up)
# baseline (speedup 1.0000x reference)
; #define LAS __attribute__((address_space(3)))
; __device__ __forceinline__ void kvprep_phase(const Frame& F, const float* kw) {
;     const bf16* KVRAW = (const bf16*)(F.ws + AR_KVRAW); const bf16* KR = (const bf16*)(F.ws + AR_KR); const float* CT = (const float*)(F.ws + WS_COS); const float* ST = (const float*)(F.ws + WS_SIN);
;     unsigned char* KH = F.ws + AR_KH; unsigned char* VT = F.ws + AR_VT;
;     LAS bf16* VS = (LAS bf16*)(F.lds + RING_OFF);
;     const int kk = F.tid >> 3, j = F.tid & 7, sz = (kk >> 1) & 7;
;     f32x4 wa[2], wb[2], wr1[2], wr2[2];
;     wa[0] = *(const f32x4*)(kw + 8 * j); wa[1] = *(const f32x4*)(kw + 8 * j + 4); wb[0] = *(const f32x4*)(kw + 64 + 8 * j); wb[1] = *(const f32x4*)(kw + 64 + 8 * j + 4);
;     wr1[0] = *(const f32x4*)(kw + 128 + 8 * (j & 3)); wr1[1] = *(const f32x4*)(kw + 128 + 8 * (j & 3) + 4); wr2[0] = *(const f32x4*)(kw + 160 + 8 * (j & 3)); wr2[1] = *(const f32x4*)(kw + 160 + 8 * (j & 3) + 4);
;     ...
;     for (int item = F.vcu; item < NKT * NH; item += F.G) {
;         const int t = item >> 4, h = item & 15;
;         const int p = 64 * t + kk; const bool valid = p < LTOT; const int r = p < 16 ? SEQ + p : p - 16;
;         v4u ka = {0u, 0u, 0u, 0u}, kb = ka, k1 = ka, k2 = ka; f32x4 c0 = {1.f, 1.f, 1.f, 1.f}, c1 = c0, s0 = {0.f, 0.f, 0.f, 0.f}, s1 = s0;
;         if (valid) { const bf16* src = KVRAW + (size_t)r * 4096 + h * 256; ka = *(const v4u*)(src + 8 * j); kb = *(const v4u*)(src + 64 + 8 * j);
;             if (j < 4) { k1 = *(const v4u*)(KR + (size_t)r * RD + 8 * j); k2 = *(const v4u*)(KR + (size_t)r * RD + 32 + 8 * j);
;                 c0 = *(const f32x4*)(CT + (size_t)p * 32 + 8 * j); c1 = *(const f32x4*)(CT + (size_t)p * 32 + 8 * j + 4); s0 = *(const f32x4*)(ST + (size_t)p * 32 + 8 * j); s1 = *(const f32x4*)(ST + (size_t)p * 32 + 8 * j + 4); } }
.LBB0_930:
	s_cmp_lt_i32 s96, 9
	s_cselect_b64 s[6:7], -1, 0
	s_and_b64 s[0:1], s[6:7], s[0:1]
	v_mov_b32_e32 v34, v0
	s_andn2_b64 vcc, exec, s[0:1]
	s_cbranch_vccnz .LBB0_946
	s_cmpk_gt_i32 s88, 0x100f
	s_cbranch_scc1 .LBB0_946
	v_lshlrev_b32_e32 v2, 5, v34
	v_and_b32_e32 v37, 7, v34
	v_and_b32_e32 v35, 0x60, v2
	v_lshlrev_b32_e32 v74, 5, v37
	s_waitcnt lgkmcnt(0)
	global_load_dwordx4 v[2:5], v35, s[66:67] offset:640
	global_load_dwordx4 v[6:9], v35, s[66:67] offset:656
	global_load_dwordx4 v[10:13], v35, s[66:67] offset:512
	global_load_dwordx4 v[14:17], v35, s[66:67] offset:528
	global_load_dwordx4 v[18:21], v74, s[66:67] offset:256
	global_load_dwordx4 v[22:25], v74, s[66:67] offset:272
	global_load_dwordx4 v[26:29], v74, s[66:67]
	global_load_dwordx4 v[30:33], v74, s[66:67] offset:16
	v_mov_b32_e32 v75, 0
	v_lshl_add_u64 v[38:39], s[50:51], 0, v[74:75]
	s_mov_b64 s[0:1], 0x110000
	v_ashrrev_i32_e32 v1, 3, v34
	v_lshl_add_u64 v[76:77], v[38:39], 0, s[0:1]
	s_mov_b64 s[0:1], 0x410000
	s_movk_i32 s3, 0x180
	v_lshl_add_u64 v[78:79], v[38:39], 0, s[0:1]
	v_mul_lo_u32 v38, v1, s3
	v_ashrrev_i32_e32 v39, 31, v38
	v_lshrrev_b32_e32 v40, 4, v34
	v_lshl_add_u64 v[38:39], s[50:51], 0, v[38:39]
	s_mov_b64 s[4:5], 0x4ce10000
	v_bfe_u32 v41, v34, 4, 3
	v_lshl_add_u64 v[80:81], v[38:39], 0, s[4:5]
	v_bitop3_b32 v38, v40, v34, 7 bitop3:0x28
	v_lshlrev_b32_e32 v35, 3, v34
	v_lshlrev_b32_e32 v82, 4, v38
	v_bitop3_b32 v38, v37, v41, 4 bitop3:0x36
	v_ashrrev_i32_e32 v87, 4, v34
	s_movk_i32 s3, 0x110
	v_lshlrev_b32_e32 v84, 4, v38
	v_and_b32_e32 v86, 0x78, v35
	v_add_u32_e32 v38, 0x200, v34
	v_mul_lo_u32 v35, v87, s3
	v_ashrrev_i32_e32 v100, 4, v38
	v_add_u32_e32 v41, 0, v35
	v_lshlrev_b32_e32 v35, 4, v34
	v_and_b32_e32 v42, 0xf0, v35
	v_mul_lo_u32 v35, v100, s3
	v_ashrrev_i32_e32 v38, 3, v38
	v_add_u32_e32 v43, 0, v35
	v_xor_b32_e32 v35, v40, v34
	v_lshl_add_u32 v45, v38, 1, 0
	v_mbcnt_lo_u32_b32 v38, -1, 0
	v_lshlrev_b32_e32 v39, 3, v35
	v_lshlrev_b32_e32 v35, 2, v35
	v_mbcnt_hi_u32_b32 v38, -1, v38
	v_and_b32_e32 v35, 4, v35
	v_and_b32_e32 v46, 64, v38
	v_and_or_b32 v35, v39, 48, v35
	v_xor_b32_e32 v39, 1, v38
	v_add_u32_e32 v46, 64, v46
	v_cmp_lt_i32_e32 vcc, v39, v46
	v_lshlrev_b32_e32 v74, 4, v37
	v_mul_u32_u24_e32 v44, 0x110, v35
	v_cndmask_b32_e32 v39, v38, v39, vcc
	v_lshlrev_b32_e32 v101, 2, v39
	v_xor_b32_e32 v39, 2, v38
	v_cmp_lt_i32_e32 vcc, v39, v46
	v_ashrrev_i32_e32 v35, 31, v34
	s_mov_b64 s[4:5], 0x49910000
	v_cndmask_b32_e32 v39, v38, v39, vcc
	v_lshlrev_b32_e32 v102, 2, v39
	v_xor_b32_e32 v39, 4, v38
	v_cmp_lt_i32_e32 vcc, v39, v46
	s_add_u32 s8, s50, 0x2e710000
	v_lshlrev_b32_e32 v36, 3, v37
	v_cndmask_b32_e32 v38, v38, v39, vcc
	v_lshlrev_b32_e32 v103, 2, v38
	v_lshl_add_u64 v[38:39], s[50:51], 0, v[74:75]
	v_lshl_add_u32 v40, v1, 1, 0
	v_lshl_add_u64 v[88:89], v[38:39], 0, s[4:5]
	v_lshl_add_u64 v[34:35], v[34:35], 4, s[50:51]
	s_mov_b64 s[4:5], 0x52f10000
	s_addc_u32 s9, s51, 0
	v_cmp_gt_u32_e64 s[0:1], 4, v37
	v_mov_b32_e32 v83, v75
	v_mov_b32_e32 v85, v75
	s_mov_b32 s11, 0
	v_lshl_add_u64 v[90:91], v[34:35], 0, s[4:5]
	s_movk_i32 s3, 0x400f
	v_lshlrev_b32_e32 v74, 1, v36
	s_movk_i32 s14, 0x4010
	v_mov_b32_e32 v104, 0x358637bd
	s_mov_b32 s15, 0xf800000
	v_mov_b32_e32 v105, 0x260
	v_add_u32_e32 v106, v41, v42
	v_add_u32_e32 v107, v43, v42
	v_add_u32_e32 v108, v40, v44
	s_mov_b32 s16, 0x5040100
	v_add_u32_e32 v109, v45, v44
	v_mov_b32_e32 v110, 0x4000
	v_mov_b32_e32 v111, 0x6000
	s_mov_b32 s17, s88
	v_mov_b32_e32 v200, s8
	v_mov_b32_e32 v201, s9
	v_mov_b64_e32 v[202:203], v[200:201]
	v_mov_b64_e32 v[204:205], v[200:201]
	s_mov_b64 s[98:99], 0x800000
	s_branch .LBB0_934

; __device__ __forceinline__ void kvprep_phase(const Frame& F, const float* kw) {
;     ...
;     for (int item = F.vcu; item < NKT * NH; item += F.G) {
;         const int t = item >> 4, h = item & 15;
;         const int p = 64 * t + kk; const bool valid = p < LTOT; const int r = p < 16 ? SEQ + p : p - 16;
;         v4u ka = {0u, 0u, 0u, 0u}, kb = ka, k1 = ka, k2 = ka; f32x4 c0 = {1.f, 1.f, 1.f, 1.f}, c1 = c0, s0 = {0.f, 0.f, 0.f, 0.f}, s1 = s0;
;         if (valid) { const bf16* src = KVRAW + (size_t)r * 4096 + h * 256; ka = *(const v4u*)(src + 8 * j); kb = *(const v4u*)(src + 64 + 8 * j);
;             if (j < 4) { k1 = *(const v4u*)(KR + (size_t)r * RD + 8 * j); k2 = *(const v4u*)(KR + (size_t)r * RD + 32 + 8 * j);
;                 c0 = *(const f32x4*)(CT + (size_t)p * 32 + 8 * j); c1 = *(const f32x4*)(CT + (size_t)p * 32 + 8 * j + 4); s0 = *(const f32x4*)(ST + (size_t)p * 32 + 8 * j); s1 = *(const f32x4*)(ST + (size_t)p * 32 + 8 * j + 4); } }
.LBB0_934:
	s_ashr_i32 s18, s17, 4
	s_lshl_b32 s20, s18, 6
	v_add_u32_e32 v36, s20, v1
	s_and_b32 s19, s17, 15
	v_cmp_lt_i32_e32 vcc, s3, v36
	s_and_saveexec_b64 s[4:5], vcc
	s_xor_b64 s[4:5], exec, s[4:5]
	s_lshl_b32 s10, s19, 8
	s_or_saveexec_b64 s[4:5], s[4:5]
	v_mov_b32_e32 v62, 0
	v_mov_b32_e32 v46, 1.0
	v_mov_b32_e32 v34, 0
	v_mov_b64_e32 v[70:71], s[10:11]
	v_mov_b32_e32 v50, 0
	v_mov_b32_e32 v51, 0
	v_mov_b32_e32 v52, 0
	v_mov_b32_e32 v53, 0
	v_mov_b32_e32 v42, 0
	v_mov_b32_e32 v43, 0
	v_mov_b32_e32 v44, 0
	v_mov_b32_e32 v45, 0
	v_mov_b32_e32 v47, 1.0
	v_mov_b32_e32 v48, 1.0
	v_mov_b32_e32 v49, 1.0
	v_mov_b32_e32 v38, 1.0
	v_mov_b32_e32 v39, 1.0
	v_mov_b32_e32 v40, 1.0
	v_mov_b32_e32 v41, 1.0
	v_mov_b32_e32 v63, 0
	v_mov_b32_e32 v64, 0
	v_mov_b32_e32 v65, 0
	v_mov_b32_e32 v66, 0
	v_mov_b32_e32 v67, 0
	v_mov_b32_e32 v68, 0
	v_mov_b32_e32 v69, 0
	v_mov_b32_e32 v58, 0
	v_mov_b32_e32 v59, 0
	v_mov_b32_e32 v60, 0
	v_mov_b32_e32 v61, 0
	v_mov_b32_e32 v54, 0
	v_mov_b32_e32 v55, 0
	v_mov_b32_e32 v56, 0
	v_mov_b32_e32 v57, 0
	s_xor_b64 exec, exec, s[4:5]
	s_cbranch_execz .LBB0_940
	v_cmp_gt_i32_e32 vcc, 16, v36
	s_lshl_b32 s10, s19, 9
	v_mov_b32_e32 v45, 0
	v_cndmask_b32_e32 v35, -16, v110, vcc
	v_add_u32_e32 v70, v35, v36
	v_ashrrev_i32_e32 v71, 31, v70
	v_lshlrev_b64 v[38:39], 13, v[70:71]
	v_lshl_add_u64 v[38:39], s[8:9], 0, v[38:39]
	v_lshl_add_u64 v[38:39], v[38:39], 0, s[10:11]
	v_lshl_add_u64 v[38:39], v[38:39], 0, v[74:75]
	v_mov_b64_e32 v[200:201], v[38:39]
	global_load_dwordx4 v[54:57], v[38:39], off
	global_load_dwordx4 v[58:61], v[38:39], off offset:128
	v_mov_b32_e32 v41, 1.0
	v_mov_b32_e32 v69, 0
	v_mov_b32_e32 v68, 0
	v_mov_b32_e32 v67, 0
	v_mov_b32_e32 v66, 0
	v_mov_b32_e32 v65, 0
	v_mov_b32_e32 v64, 0
	v_mov_b32_e32 v63, 0
	v_mov_b32_e32 v62, 0
	v_mov_b32_e32 v40, 1.0
	v_mov_b32_e32 v39, 1.0
	v_mov_b32_e32 v38, 1.0
	v_mov_b32_e32 v49, 1.0
	v_mov_b32_e32 v48, 1.0
	v_mov_b32_e32 v47, 1.0
	v_mov_b32_e32 v46, 1.0
	v_mov_b32_e32 v44, 0
	v_mov_b32_e32 v43, 0
	v_mov_b32_e32 v42, 0
	v_mov_b32_e32 v53, 0
	v_mov_b32_e32 v52, 0
	v_mov_b32_e32 v51, 0
	v_mov_b32_e32 v50, 0
	s_and_saveexec_b64 s[12:13], s[0:1]
	s_cbranch_execz .LBB0_939
	v_ashrrev_i32_e32 v37, 31, v36
	v_lshlrev_b64 v[38:39], 7, v[70:71]
	v_lshlrev_b64 v[36:37], 7, v[36:37]
	v_lshl_add_u64 v[38:39], v[88:89], 0, v[38:39]
	v_lshl_add_u64 v[42:43], v[76:77], 0, v[36:37]
	v_lshl_add_u64 v[36:37], v[78:79], 0, v[36:37]
	global_load_dwordx4 v[66:69], v[38:39], off
	global_load_dwordx4 v[62:65], v[38:39], off offset:64
	global_load_dwordx4 v[46:49], v[42:43], off offset:16
	s_nop 0
	global_load_dwordx4 v[38:41], v[42:43], off
	global_load_dwordx4 v[50:53], v[36:37], off offset:16
	s_nop 0
	global_load_dwordx4 v[42:45], v[36:37], off

; __device__ __forceinline__ void kvprep_phase(const Frame& F, const float* kw) {
;     ...
;         v4u vv[2];
; #pragma unroll
;         for (int q = 0; q < 2; ++q) { const int id = F.tid + 512 * q, vr = id >> 4, vc = id & 15, vp = 64 * t + vr; const int rr = vp < 16 ? SEQ + vp : vp - 16;
;             vv[q] = (v4u){0u, 0u, 0u, 0u}; if (vp < LTOT) vv[q] = *(const v4u*)(KVRAW + (size_t)rr * 4096 + h * 256 + 128 + 8 * vc); }
.LBB0_940:
	s_or_b64 exec, exec, s[4:5]
	v_lshl_add_u64 v[92:93], v[70:71], 1, s[8:9]
	v_add_u32_e32 v70, s20, v87
	v_cmp_gt_i32_e32 vcc, s14, v70
	v_lshlrev_b32_e32 v94, 1, v86
	v_mov_b32_e32 v35, 0
	v_mov_b32_e32 v36, 0
	v_mov_b32_e32 v37, 0
	s_and_saveexec_b64 s[4:5], vcc
	s_cbranch_execz .LBB0_942
	v_cmp_gt_i32_e32 vcc, 16, v70
	v_mov_b32_e32 v95, v75
	s_nop 0
	v_cndmask_b32_e32 v34, -16, v110, vcc
	v_add_u32_e32 v34, v34, v70
	v_ashrrev_i32_e32 v35, 31, v34
	v_lshlrev_b64 v[34:35], 13, v[34:35]
	v_lshl_add_u64 v[34:35], v[92:93], 0, v[34:35]
	v_lshl_add_u64 v[34:35], v[34:35], 0, v[94:95]
	v_mov_b64_e32 v[202:203], v[34:35]
	global_load_dwordx4 v[34:37], v[34:35], off offset:256
.LBB0_942:
	s_or_b64 exec, exec, s[4:5]
	v_add_u32_e32 v95, s20, v100
	v_cmp_gt_i32_e32 vcc, s14, v95
	v_mov_b32_e32 v70, 0
	v_mov_b32_e32 v71, 0
	v_mov_b32_e32 v72, 0
	v_mov_b32_e32 v73, 0
	s_and_saveexec_b64 s[4:5], vcc
	s_cbranch_execz .LBB0_944
	v_cmp_gt_i32_e32 vcc, 16, v95
	s_nop 1
	v_cndmask_b32_e32 v70, -16, v110, vcc
	v_add_u32_e32 v70, v70, v95
	v_ashrrev_i32_e32 v71, 31, v70
	v_lshlrev_b64 v[70:71], 13, v[70:71]
	v_lshl_add_u64 v[70:71], v[92:93], 0, v[70:71]
	v_mov_b32_e32 v95, v75
	v_lshl_add_u64 v[70:71], v[70:71], 0, v[94:95]
	v_mov_b64_e32 v[204:205], v[70:71]
	global_load_dwordx4 v[70:73], v[70:71], off offset:256
.LBB0_944:
	s_or_b64 exec, exec, s[4:5]
	s_waitcnt vmcnt(0)
	s_add_i32 s100, s17, s68
	s_cmpk_lt_i32 s100, 0x1010
	s_cbranch_scc0 .Lmy_kv_nopf
	v_lshl_add_u64 v[206:207], v[200:201], 0, s[98:99]
	v_lshl_add_u64 v[208:209], v[202:203], 0, s[98:99]
	v_lshl_add_u64 v[210:211], v[204:205], 0, s[98:99]
	global_load_dword v216, v[206:207], off
	global_load_dword v217, v[206:207], off offset:128
	global_load_dword v218, v[208:209], off offset:256
	global_load_dword v219, v[210:211], off offset:256
; #define KV_UNPK(w_, f_) do { f_[0] = bflo(w_.x); f_[1] = bfhi(w_.x); f_[2] = bflo(w_.y); f_[3] = bfhi(w_.y); f_[4] = bflo(w_.z); f_[5] = bfhi(w_.z); f_[6] = bflo(w_.w); f_[7] = bfhi(w_.w); } while (0)
; #define KV_PK(f_) ((v4u){pk_bf16(f_[0], f_[1]), pk_bf16(f_[2], f_[3]), pk_bf16(f_[4], f_[5]), pk_bf16(f_[6], f_[7])})
; __device__ __forceinline__ void kvprep_phase(const Frame& F, const float* kw) {
;     ...
;         float fa[8], fb[8], f1[8], f2[8];
;         KV_UNPK(ka, fa); KV_UNPK(kb, fb); KV_UNPK(k1, f1); KV_UNPK(k2, f2);
;         float ss = 0.f;
; #pragma unroll
;         for (int e = 0; e < 8; ++e) ss += fa[e] * fa[e] + fb[e] * fb[e] + f1[e] * f1[e] + f2[e] * f2[e];
;         ss += __shfl_xor(ss, 1); ss += __shfl_xor(ss, 2); ss += __shfl_xor(ss, 4);
;         const float rstd = 1.0f / sqrtf(ss * (1.0f / QKD) + EPS);
;         const float ga[8] = {wa[0][0], wa[0][1], wa[0][2], wa[0][3], wa[1][0], wa[1][1], wa[1][2], wa[1][3]}, gb[8] = {wb[0][0], wb[0][1], wb[0][2], wb[0][3], wb[1][0], wb[1][1], wb[1][2], wb[1][3]};
;         const float g1[8] = {wr1[0][0], wr1[0][1], wr1[0][2], wr1[0][3], wr1[1][0], wr1[1][1], wr1[1][2], wr1[1][3]}, g2[8] = {wr2[0][0], wr2[0][1], wr2[0][2], wr2[0][3], wr2[1][0], wr2[1][1], wr2[1][2], wr2[1][3]};
;         const float cc[8] = {c0[0], c0[1], c0[2], c0[3], c1[0], c1[1], c1[2], c1[3]}, sn[8] = {s0[0], s0[1], s0[2], s0[3], s1[0], s1[1], s1[2], s1[3]};
;         float y1[8], y2[8];
; #pragma unroll
;         for (int e = 0; e < 8; ++e) { fa[e] *= rstd * ga[e]; fb[e] *= rstd * gb[e]; const float x1 = f1[e] * rstd * g1[e], x2 = f2[e] * rstd * g2[e]; y1[e] = x1 * cc[e] - x2 * sn[e]; y2[e] = x2 * cc[e] + x1 * sn[e]; }
;         { unsigned char* kimg = KH + (size_t)(h * NKT + t) * 24576 + kk * 384;
;           *(v4u*)(kimg + ((j ^ sz) << 4)) = KV_PK(fa);
;           *(v4u*)(kimg + 128 + ((j ^ sz) << 4)) = KV_PK(fb);
;           if (j < 4) { *(v4u*)(kimg + 256 + ((j ^ sz) << 4)) = KV_PK(y1);
;                        *(v4u*)(kimg + 256 + (((4 + j) ^ sz) << 4)) = KV_PK(y2); } }
.Lmy_kv_nopf:
	v_lshlrev_b32_e32 v120, 16, v59
	v_and_b32_e32 v121, 0xffff0000, v59
	v_lshlrev_b32_e32 v126, 16, v58
	v_and_b32_e32 v127, 0xffff0000, v58
	v_lshlrev_b32_e32 v58, 16, v54
	v_and_b32_e32 v59, 0xffff0000, v54
	v_lshlrev_b32_e32 v122, 16, v55
	v_and_b32_e32 v123, 0xffff0000, v55
	v_pk_mul_f32 v[54:55], v[58:59], v[58:59]
	v_lshlrev_b32_e32 v92, 16, v66
	v_and_b32_e32 v93, 0xffff0000, v66
	v_pk_mul_f32 v[124:125], v[122:123], v[122:123]
	v_pk_fma_f32 v[54:55], v[126:127], v[126:127], v[54:55]
	v_lshlrev_b32_e32 v94, 16, v62
	v_and_b32_e32 v95, 0xffff0000, v62
	v_lshlrev_b32_e32 v66, 16, v67
	v_and_b32_e32 v67, 0xffff0000, v67
	v_lshlrev_b32_e32 v112, 16, v61
	v_and_b32_e32 v113, 0xffff0000, v61
	v_lshlrev_b32_e32 v118, 16, v60
	v_and_b32_e32 v119, 0xffff0000, v60
	v_lshlrev_b32_e32 v60, 16, v56
	v_and_b32_e32 v61, 0xffff0000, v56
	v_pk_fma_f32 v[124:125], v[120:121], v[120:121], v[124:125]
	v_pk_fma_f32 v[54:55], v[92:93], v[92:93], v[54:55]
	v_lshlrev_b32_e32 v62, 16, v63
	v_and_b32_e32 v63, 0xffff0000, v63
	v_lshlrev_b32_e32 v114, 16, v57
	v_and_b32_e32 v115, 0xffff0000, v57
	v_pk_mul_f32 v[56:57], v[60:61], v[60:61]
	v_pk_fma_f32 v[124:125], v[66:67], v[66:67], v[124:125]
	v_pk_fma_f32 v[54:55], v[94:95], v[94:95], v[54:55]
	v_lshlrev_b32_e32 v96, 16, v68
	v_and_b32_e32 v97, 0xffff0000, v68
	v_pk_fma_f32 v[56:57], v[118:119], v[118:119], v[56:57]
	v_pk_fma_f32 v[124:125], v[62:63], v[62:63], v[124:125]
	v_add_f32_e32 v54, v54, v55
	v_lshlrev_b32_e32 v98, 16, v64
	v_and_b32_e32 v99, 0xffff0000, v64
	v_pk_mul_f32 v[116:117], v[114:115], v[114:115]
	v_pk_fma_f32 v[56:57], v[96:97], v[96:97], v[56:57]
	v_add_f32_e32 v54, v124, v54
	v_lshlrev_b32_e32 v68, 16, v69
	v_and_b32_e32 v69, 0xffff0000, v69
	v_pk_fma_f32 v[116:117], v[112:113], v[112:113], v[116:117]
	v_pk_fma_f32 v[56:57], v[98:99], v[98:99], v[56:57]
	v_add_f32_e32 v54, v125, v54
	v_lshlrev_b32_e32 v64, 16, v65
	v_and_b32_e32 v65, 0xffff0000, v65
	v_pk_fma_f32 v[116:117], v[68:69], v[68:69], v[116:117]
	v_add_f32_e32 v54, v56, v54
	v_pk_fma_f32 v[116:117], v[64:65], v[64:65], v[116:117]
	v_add_f32_e32 v54, v57, v54
	v_add_f32_e32 v54, v116, v54
	v_add_f32_e32 v54, v117, v54
	ds_bpermute_b32 v55, v101, v54
	s_waitcnt lgkmcnt(0)
	v_add_f32_e32 v54, v54, v55
	ds_bpermute_b32 v55, v102, v54
	s_waitcnt lgkmcnt(0)
	v_add_f32_e32 v54, v54, v55
	ds_bpermute_b32 v55, v103, v54
	s_waitcnt lgkmcnt(0)
	v_add_f32_e32 v54, v54, v55
	v_fmamk_f32 v54, v54, 0x3baaaaab, v104
	v_mul_f32_e32 v55, 0x4f800000, v54
	v_cmp_gt_f32_e32 vcc, s15, v54
	s_nop 1
	v_cndmask_b32_e32 v54, v54, v55, vcc
	v_sqrt_f32_e32 v55, v54
	s_nop 0
	v_add_u32_e32 v56, -1, v55
	v_fma_f32 v57, -v56, v55, v54
	v_cmp_ge_f32_e64 s[4:5], 0, v57
	v_add_u32_e32 v57, 1, v55
	s_nop 0
	v_cndmask_b32_e64 v56, v55, v56, s[4:5]
	v_fma_f32 v55, -v57, v55, v54
	v_cmp_lt_f32_e64 s[4:5], 0, v55
	s_nop 1
	v_cndmask_b32_e64 v55, v56, v57, s[4:5]
	v_mul_f32_e32 v56, 0x37800000, v55
	v_cndmask_b32_e32 v55, v55, v56, vcc
	v_cmp_class_f32_e32 vcc, v54, v105
	s_nop 1
	v_cndmask_b32_e32 v54, v55, v54, vcc
	v_div_scale_f32 v55, s[4:5], v54, v54, 1.0
	v_rcp_f32_e32 v56, v55
	s_mul_i32 s4, s19, 0x101
	s_add_i32 s4, s4, s18
	v_fma_f32 v57, -v55, v56, 1.0
	v_fmac_f32_e32 v56, v57, v56
	v_div_scale_f32 v57, vcc, 1.0, v54, 1.0
	v_mul_f32_e32 v116, v57, v56
	v_fma_f32 v117, -v55, v116, v57
	v_fmac_f32_e32 v116, v117, v56
	v_fma_f32 v55, -v55, v116, v57
	v_div_fmas_f32 v55, v55, v56, v116
	v_div_fixup_f32 v56, v55, v54, 1.0
	v_pk_mul_f32 v[54:55], v[26:27], v[56:57] op_sel_hi:[1,0]
	s_nop 0
	v_pk_mul_f32 v[58:59], v[54:55], v[58:59]
	v_pk_mul_f32 v[54:55], v[18:19], v[56:57] op_sel_hi:[1,0]
	s_nop 0
	v_pk_mul_f32 v[116:117], v[54:55], v[126:127]
	v_pk_mul_f32 v[54:55], v[28:29], v[56:57] op_sel_hi:[1,0]
	s_nop 0
	v_pk_mul_f32 v[122:123], v[54:55], v[122:123]
	v_pk_mul_f32 v[54:55], v[20:21], v[56:57] op_sel_hi:[1,0]
	s_nop 0
	v_pk_mul_f32 v[120:121], v[54:55], v[120:121]
	v_pk_mul_f32 v[54:55], v[30:31], v[56:57] op_sel_hi:[1,0]
	s_nop 0
	v_pk_mul_f32 v[60:61], v[54:55], v[60:61]
	v_pk_mul_f32 v[54:55], v[22:23], v[56:57] op_sel_hi:[1,0]
	s_nop 0
	v_pk_mul_f32 v[118:119], v[54:55], v[118:119]
	v_pk_mul_f32 v[54:55], v[32:33], v[56:57] op_sel_hi:[1,0]
	s_nop 0
	v_pk_mul_f32 v[124:125], v[54:55], v[114:115]
	v_pk_mul_f32 v[54:55], v[24:25], v[56:57] op_sel_hi:[1,0]
	v_cvt_pk_bf16_f32 v114, v60, v61
	v_pk_mul_f32 v[126:127], v[54:55], v[112:113]
	v_mad_i64_i32 v[54:55], s[12:13], s4, v111, v[80:81]
	v_cvt_pk_bf16_f32 v112, v58, v59
	v_cvt_pk_bf16_f32 v113, v122, v123
	v_cvt_pk_bf16_f32 v115, v124, v125
	v_lshl_add_u64 v[58:59], v[54:55], 0, v[82:83]
	global_store_dwordx4 v[58:59], v[112:115], off
	s_nop 1
	v_cvt_pk_bf16_f32 v112, v116, v117
	v_cvt_pk_bf16_f32 v113, v120, v121
	v_cvt_pk_bf16_f32 v114, v118, v119
	v_cvt_pk_bf16_f32 v115, v126, v127
	global_store_dwordx4 v[58:59], v[112:115], off offset:128
	s_and_saveexec_b64 s[12:13], s[0:1]
	s_cbranch_execz .LBB0_933
	v_mov_b32_e32 v57, v56
	v_pk_mul_f32 v[60:61], v[56:57], v[64:65]
	v_pk_mul_f32 v[64:65], v[56:57], v[68:69]
	v_pk_mul_f32 v[60:61], v[8:9], v[60:61]
	v_pk_mul_f32 v[64:65], v[16:17], v[64:65]
	s_nop 0
	v_pk_mul_f32 v[68:69], v[52:53], v[64:65]
	v_pk_mul_f32 v[52:53], v[52:53], v[60:61]
	v_pk_fma_f32 v[68:69], v[48:49], v[60:61], v[68:69]
	v_pk_fma_f32 v[48:49], v[48:49], v[64:65], v[52:53] neg_lo:[0,0,1] neg_hi:[0,0,1]
	v_pk_mul_f32 v[52:53], v[56:57], v[98:99]
	v_pk_mul_f32 v[60:61], v[56:57], v[96:97]
	v_pk_mul_f32 v[52:53], v[6:7], v[52:53]
	v_pk_mul_f32 v[60:61], v[14:15], v[60:61]
	s_nop 0
	v_pk_mul_f32 v[64:65], v[50:51], v[60:61]
	v_pk_mul_f32 v[50:51], v[50:51], v[52:53]
	v_pk_fma_f32 v[64:65], v[46:47], v[52:53], v[64:65]
	v_pk_fma_f32 v[46:47], v[46:47], v[60:61], v[50:51] neg_lo:[0,0,1] neg_hi:[0,0,1]
	v_pk_mul_f32 v[50:51], v[56:57], v[62:63]
	v_pk_mul_f32 v[52:53], v[56:57], v[66:67]
	v_pk_mul_f32 v[50:51], v[4:5], v[50:51]
	v_pk_mul_f32 v[52:53], v[12:13], v[52:53]
	s_nop 0
	v_pk_mul_f32 v[60:61], v[44:45], v[52:53]
	v_pk_mul_f32 v[44:45], v[44:45], v[50:51]
	v_pk_fma_f32 v[60:61], v[40:41], v[50:51], v[60:61]
	v_pk_fma_f32 v[40:41], v[40:41], v[52:53], v[44:45] neg_lo:[0,0,1] neg_hi:[0,0,1]
	v_pk_mul_f32 v[44:45], v[56:57], v[94:95]
	v_pk_mul_f32 v[50:51], v[56:57], v[92:93]
	v_pk_mul_f32 v[44:45], v[2:3], v[44:45]
	v_pk_mul_f32 v[50:51], v[10:11], v[50:51]
	s_nop 0
	v_pk_mul_f32 v[52:53], v[42:43], v[50:51]
	v_pk_mul_f32 v[42:43], v[42:43], v[44:45]
	v_pk_fma_f32 v[52:53], v[38:39], v[44:45], v[52:53]
	v_pk_fma_f32 v[38:39], v[38:39], v[50:51], v[42:43] neg_lo:[0,0,1] neg_hi:[0,0,1]
	v_lshl_add_u64 v[42:43], v[54:55], 0, v[84:85]
	v_cvt_pk_bf16_f32 v38, v38, v39
	v_cvt_pk_bf16_f32 v39, v40, v41
	v_cvt_pk_bf16_f32 v40, v46, v47
	v_cvt_pk_bf16_f32 v41, v48, v49
	global_store_dwordx4 v[58:59], v[38:41], off offset:256
	s_nop 1
	v_cvt_pk_bf16_f32 v38, v52, v53
	v_cvt_pk_bf16_f32 v39, v60, v61
	v_cvt_pk_bf16_f32 v40, v64, v65
	v_cvt_pk_bf16_f32 v41, v68, v69
	global_store_dwordx4 v[42:43], v[38:41], off offset:256
	s_branch .LBB0_933
